# v20 + both leading vmcnt waits of the K-loop pass that follows a unit epilogue (P1, P7) are vmcnt(24) (conditional on a flag), vmcnt(8) in every other pass
# speedup vs baseline: 1.0034x; 1.0025x over previous
; #define PG8_STAGE(bufoff, gbase, voff) do { _Pragma("unroll") for (int _i = 0; _i < 2; ++_i) \
;         __builtin_amdgcn_global_load_lds((const unsigned*)((const char*)(gbase) + (voff)[_i]), (PG8_LAS unsigned*)(lds + (bufoff) + ldsw + _i * 8192), 16, 0, 0); } while (0)
; #define PG8_LDA(dst, b, h) do { _Pragma("unroll") for (int m = 0; m < 4; ++m) _Pragma("unroll") for (int k = 0; k < 2; ++k) dst[m][k] = *(const PG8_LAS bf16x8*)(lds + PG8_SA(b, h) + aoff + m * 2048 + k * 1024); } while (0)
; #define PG8_LDB(dst, b, h) do { _Pragma("unroll") for (int n = 0; n < 2; ++n) _Pragma("unroll") for (int k = 0; k < 2; ++k) dst[n][k] = *(const PG8_LAS bf16x8*)(lds + PG8_SB(b, h) + boff + n * 2048 + k * 1024); } while (0)
; #define PG8_MMA(ai, bj, At, Bt) do { __builtin_amdgcn_s_setprio(1); _Pragma("unroll") for (int m = 0; m < 4; ++m) _Pragma("unroll") for (int n = 0; n < 2; ++n) _Pragma("unroll") for (int k = 0; k < 2; ++k) \
;         acc[ai][bj][m][n] = __builtin_amdgcn_mfma_f32_16x16x32_bf16(Bt[n][k], At[m][k], acc[ai][bj][m][n], 0, 0, 0); __builtin_amdgcn_s_setprio(0); } while (0)
; #define PG8_WAIT_V(n) asm volatile("s_waitcnt vmcnt(" #n ")" ::: "memory")
; #define PG8_WAIT_L(n) asm volatile("s_waitcnt lgkmcnt(" #n ")" ::: "memory")
; #define PG8_BAR __builtin_amdgcn_s_barrier()
; #define PG8_SCHED __builtin_amdgcn_sched_barrier(0)
; template <class Epi, class Sched, bool ALIGN_EPI = false, bool SP2 = false>
; __device__ __forceinline__ void gemm_phase(PG8_LAS unsigned char* lds, const Gemm g, const Sched& S, const Epi& E) {
;     ...
;             const char* a1 = cA + (size_t)(t + 1) * kstep;
;             const char* a2 = last ? nA : cA + (size_t)(t + 2) * kstep; const char* b2 = last ? nB : cB + (size_t)(t + 2) * kstep;
;             const char* a3 = a2 + kstep; const char* b3 = b2 + kstep;
;             if (last && has_next) S.a_ready(nxt);
;             if constexpr (SP2) {
;             PG8_LDB(B0, 0, 0); PG8_LDB(B1, 0, 1); PG8_SCHED; PG8_LDA(At, 0, 0); PG8_STAGE(PG8_SA(1, 1), a1 + hstep, voffA);
;             PG8_WAIT_V(8); PG8_WAIT_L(0); PG8_BAR; PG8_MMA(0, 0, At, B0); PG8_MMA(0, 1, At, B1); PG8_BAR; PG8_SCHED;
.LBB0_192:
	ds_read_b128 v[146:149], v152
	ds_read_b128 v[156:159], v152 offset:1024
	ds_read_b128 v[160:163], v152 offset:2048
	ds_read_b128 v[164:167], v152 offset:3072
	ds_read_b128 v[168:171], v153
	ds_read_b128 v[172:175], v153 offset:1024
	ds_read_b128 v[176:179], v153 offset:2048
	ds_read_b128 v[180:183], v153 offset:3072
	s_add_u32 s22, s20, 0xfffc0080
	s_addc_u32 s23, s21, -1
	s_cmp_eq_u32 s75, 12
	s_cselect_b32 s25, s5, s23
	s_cselect_b32 s24, s13, s22
	s_cselect_b32 s23, s11, s74
	s_cselect_b32 s22, s19, s73
	v_lshl_add_u64 v[216:217], s[20:21], 0, v[138:139]
	s_add_i32 m0, s27, 0xc000
	ds_read_b128 v[184:187], v154
	ds_read_b128 v[188:191], v154 offset:1024
	ds_read_b128 v[192:195], v154 offset:2048
	ds_read_b128 v[196:199], v154 offset:3072
	ds_read_b128 v[200:203], v154 offset:4096
	ds_read_b128 v[204:207], v154 offset:5120
	ds_read_b128 v[208:211], v154 offset:6144
	ds_read_b128 v[212:215], v154 offset:7168
	global_load_lds_dwordx4 v[216:217], off
	v_lshl_add_u64 v[216:217], s[20:21], 0, v[140:141]
	s_add_i32 m0, s27, 0xe000
	s_nop 0
	global_load_lds_dwordx4 v[216:217], off
	s_cmp_lg_u32 s101, 0
	s_cbranch_scc1 .Lry1
	s_waitcnt vmcnt(8)
	s_branch .Lrk1

; #define PG8_STAGE(bufoff, gbase, voff) do { _Pragma("unroll") for (int _i = 0; _i < 2; ++_i) \
;         __builtin_amdgcn_global_load_lds((const unsigned*)((const char*)(gbase) + (voff)[_i]), (PG8_LAS unsigned*)(lds + (bufoff) + ldsw + _i * 8192), 16, 0, 0); } while (0)
; #define PG8_LDA(dst, b, h) do { _Pragma("unroll") for (int m = 0; m < 4; ++m) _Pragma("unroll") for (int k = 0; k < 2; ++k) dst[m][k] = *(const PG8_LAS bf16x8*)(lds + PG8_SA(b, h) + aoff + m * 2048 + k * 1024); } while (0)
; #define PG8_MMA(ai, bj, At, Bt) do { __builtin_amdgcn_s_setprio(1); _Pragma("unroll") for (int m = 0; m < 4; ++m) _Pragma("unroll") for (int n = 0; n < 2; ++n) _Pragma("unroll") for (int k = 0; k < 2; ++k) \
;         acc[ai][bj][m][n] = __builtin_amdgcn_mfma_f32_16x16x32_bf16(Bt[n][k], At[m][k], acc[ai][bj][m][n], 0, 0, 0); __builtin_amdgcn_s_setprio(0); } while (0)
; #define PG8_WAIT_V(n) asm volatile("s_waitcnt vmcnt(" #n ")" ::: "memory")
; #define PG8_WAIT_L(n) asm volatile("s_waitcnt lgkmcnt(" #n ")" ::: "memory")
; #define PG8_BAR __builtin_amdgcn_s_barrier()
; #define PG8_SCHED __builtin_amdgcn_sched_barrier(0)
; template <class Epi, class Sched, bool ALIGN_EPI = false, bool SP2 = false>
; __device__ __forceinline__ void gemm_phase(PG8_LAS unsigned char* lds, const Gemm g, const Sched& S, const Epi& E) {
;     ...
;             PG8_WAIT_V(8); PG8_WAIT_L(0); PG8_BAR; PG8_MMA(0, 0, At, B0); PG8_MMA(0, 1, At, B1); PG8_BAR; PG8_SCHED;
;             PG8_LDA(At, 0, 1); PG8_STAGE(PG8_SB(0, 0), b2, voffB); PG8_STAGE(PG8_SB(0, 1), b2 + hstepB, voffB); PG8_STAGE(PG8_SA(0, 0), a2, voffA);
.Lrk1:
	s_waitcnt lgkmcnt(0)
	s_barrier
	v_mfma_f32_16x16x32_bf16 v[126:129], v[146:149], v[184:187], v[126:129]
	v_mfma_f32_16x16x32_bf16 v[122:125], v[160:163], v[184:187], v[122:125]
	v_mfma_f32_16x16x32_bf16 v[114:117], v[146:149], v[192:195], v[114:117]
	v_mfma_f32_16x16x32_bf16 v[106:109], v[160:163], v[192:195], v[106:109]
	v_mfma_f32_16x16x32_bf16 v[98:101], v[146:149], v[200:203], v[98:101]
	v_mfma_f32_16x16x32_bf16 v[90:93], v[160:163], v[200:203], v[90:93]
	v_mfma_f32_16x16x32_bf16 v[82:85], v[146:149], v[208:211], v[82:85]
	v_mfma_f32_16x16x32_bf16 v[74:77], v[160:163], v[208:211], v[74:77]
	v_mfma_f32_16x16x32_bf16 v[126:129], v[156:159], v[188:191], v[126:129]
	v_mfma_f32_16x16x32_bf16 v[122:125], v[164:167], v[188:191], v[122:125]
	v_mfma_f32_16x16x32_bf16 v[114:117], v[156:159], v[196:199], v[114:117]
	v_mfma_f32_16x16x32_bf16 v[106:109], v[164:167], v[196:199], v[106:109]
	v_mfma_f32_16x16x32_bf16 v[98:101], v[156:159], v[204:207], v[98:101]
	v_mfma_f32_16x16x32_bf16 v[90:93], v[164:167], v[204:207], v[90:93]
	v_mfma_f32_16x16x32_bf16 v[82:85], v[156:159], v[212:215], v[82:85]
	v_mfma_f32_16x16x32_bf16 v[74:77], v[164:167], v[212:215], v[74:77]
	v_mfma_f32_16x16x32_bf16 v[118:121], v[168:171], v[184:187], v[118:121]
	v_mfma_f32_16x16x32_bf16 v[110:113], v[176:179], v[184:187], v[110:113]
	v_mfma_f32_16x16x32_bf16 v[102:105], v[168:171], v[192:195], v[102:105]
	v_mfma_f32_16x16x32_bf16 v[94:97], v[176:179], v[192:195], v[94:97]
	v_mfma_f32_16x16x32_bf16 v[86:89], v[168:171], v[200:203], v[86:89]
	v_mfma_f32_16x16x32_bf16 v[78:81], v[176:179], v[200:203], v[78:81]
	v_mfma_f32_16x16x32_bf16 v[70:73], v[168:171], v[208:211], v[70:73]
	v_mfma_f32_16x16x32_bf16 v[66:69], v[176:179], v[208:211], v[66:69]
	v_mfma_f32_16x16x32_bf16 v[118:121], v[172:175], v[188:191], v[118:121]
	v_mfma_f32_16x16x32_bf16 v[110:113], v[180:183], v[188:191], v[110:113]
	v_mfma_f32_16x16x32_bf16 v[102:105], v[172:175], v[196:199], v[102:105]
	v_mfma_f32_16x16x32_bf16 v[94:97], v[180:183], v[196:199], v[94:97]
	v_mfma_f32_16x16x32_bf16 v[86:89], v[172:175], v[204:207], v[86:89]
	v_mfma_f32_16x16x32_bf16 v[78:81], v[180:183], v[204:207], v[78:81]
	v_mfma_f32_16x16x32_bf16 v[70:73], v[172:175], v[212:215], v[70:73]
	v_mfma_f32_16x16x32_bf16 v[66:69], v[180:183], v[212:215], v[66:69]
	s_barrier
	s_add_i32 s76, s69, s26
	v_lshl_add_u64 v[216:217], s[22:23], 0, v[132:133]
	s_mov_b32 m0, s76
	ds_read_b128 v[184:187], v154 offset:16384
	ds_read_b128 v[188:191], v154 offset:17408
	ds_read_b128 v[192:195], v154 offset:18432
	ds_read_b128 v[196:199], v154 offset:19456
	ds_read_b128 v[200:203], v154 offset:20480
	ds_read_b128 v[204:207], v154 offset:21504
	ds_read_b128 v[208:211], v154 offset:22528
	ds_read_b128 v[212:215], v154 offset:23552
	global_load_lds_dwordx4 v[216:217], off
	s_add_i32 m0, s76, 0x2000
	s_add_u32 s76, s22, 0x10000
	v_lshl_add_u64 v[218:219], s[22:23], 0, v[136:137]
	s_addc_u32 s77, s23, 0
	s_add_i32 s78, s70, s26
	global_load_lds_dwordx4 v[218:219], off
	v_lshl_add_u64 v[220:221], s[76:77], 0, v[132:133]
	s_mov_b32 m0, s78
	v_lshl_add_u64 v[222:223], s[24:25], 0, v[134:135]
	global_load_lds_dwordx4 v[220:221], off
	v_lshl_add_u64 v[220:221], s[76:77], 0, v[136:137]
	s_add_i32 m0, s78, 0x2000
	s_nop 0
	global_load_lds_dwordx4 v[220:221], off
	v_lshl_add_u64 v[220:221], s[24:25], 0, v[130:131]
	s_mov_b32 m0, s27
	s_nop 0
	global_load_lds_dwordx4 v[220:221], off
	s_mov_b32 m0, s28
	s_nop 0
	global_load_lds_dwordx4 v[222:223], off
	s_cmp_lg_u32 s101, 0
	s_cbranch_scc1 .Lrx1
	s_waitcnt vmcnt(8)
	s_branch .Lrj1

; #define PG8_STAGE(bufoff, gbase, voff) do { _Pragma("unroll") for (int _i = 0; _i < 2; ++_i) \
;         __builtin_amdgcn_global_load_lds((const unsigned*)((const char*)(gbase) + (voff)[_i]), (PG8_LAS unsigned*)(lds + (bufoff) + ldsw + _i * 8192), 16, 0, 0); } while (0)
; #define PG8_LDA(dst, b, h) do { _Pragma("unroll") for (int m = 0; m < 4; ++m) _Pragma("unroll") for (int k = 0; k < 2; ++k) dst[m][k] = *(const PG8_LAS bf16x8*)(lds + PG8_SA(b, h) + aoff + m * 2048 + k * 1024); } while (0)
; #define PG8_LDB(dst, b, h) do { _Pragma("unroll") for (int n = 0; n < 2; ++n) _Pragma("unroll") for (int k = 0; k < 2; ++k) dst[n][k] = *(const PG8_LAS bf16x8*)(lds + PG8_SB(b, h) + boff + n * 2048 + k * 1024); } while (0)
; #define PG8_MMA(ai, bj, At, Bt) do { __builtin_amdgcn_s_setprio(1); _Pragma("unroll") for (int m = 0; m < 4; ++m) _Pragma("unroll") for (int n = 0; n < 2; ++n) _Pragma("unroll") for (int k = 0; k < 2; ++k) \
;         acc[ai][bj][m][n] = __builtin_amdgcn_mfma_f32_16x16x32_bf16(Bt[n][k], At[m][k], acc[ai][bj][m][n], 0, 0, 0); __builtin_amdgcn_s_setprio(0); } while (0)
; #define PG8_WAIT_V(n) asm volatile("s_waitcnt vmcnt(" #n ")" ::: "memory")
; #define PG8_WAIT_L(n) asm volatile("s_waitcnt lgkmcnt(" #n ")" ::: "memory")
; #define PG8_BAR __builtin_amdgcn_s_barrier()
; #define PG8_SCHED __builtin_amdgcn_sched_barrier(0)
; template <class Epi, class Sched, bool ALIGN_EPI = false, bool SP2 = false>
; __device__ __forceinline__ void gemm_phase(PG8_LAS unsigned char* lds, const Gemm g, const Sched& S, const Epi& E) {
;     ...
;             const char* a1 = cA + (size_t)(t + 1) * kstep;
;             const char* a2 = last ? nA : cA + (size_t)(t + 2) * kstep; const char* b2 = last ? nB : cB + (size_t)(t + 2) * kstep;
;             const char* a3 = a2 + kstep; const char* b3 = b2 + kstep;
;             if (last && has_next) S.a_ready(nxt);
;             if constexpr (SP2) {
;             PG8_LDB(B0, 0, 0); PG8_LDB(B1, 0, 1); PG8_SCHED; PG8_LDA(At, 0, 0); PG8_STAGE(PG8_SA(1, 1), a1 + hstep, voffA);
;             PG8_WAIT_V(8); PG8_WAIT_L(0); PG8_BAR; PG8_MMA(0, 0, At, B0); PG8_MMA(0, 1, At, B1); PG8_BAR; PG8_SCHED;
.LBB0_1313:
	ds_read_b128 v[146:149], v154
	ds_read_b128 v[158:161], v154 offset:1024
	ds_read_b128 v[162:165], v154 offset:2048
	ds_read_b128 v[166:169], v154 offset:3072
	ds_read_b128 v[170:173], v155
	ds_read_b128 v[174:177], v155 offset:1024
	ds_read_b128 v[178:181], v155 offset:2048
	ds_read_b128 v[182:185], v155 offset:3072
	s_add_u32 s40, s38, 0xfffc0080
	s_addc_u32 s41, s39, -1
	s_cmp_eq_u32 s61, 12
	s_cselect_b32 s43, s9, s41
	s_cselect_b32 s42, s27, s40
	s_cselect_b32 s41, s25, s60
	s_cselect_b32 s40, s37, s59
	v_lshl_add_u64 v[150:151], s[38:39], 0, v[138:139]
	s_add_i32 m0, s31, 0xc000
	ds_read_b128 v[186:189], v156
	ds_read_b128 v[190:193], v156 offset:1024
	ds_read_b128 v[194:197], v156 offset:2048
	ds_read_b128 v[198:201], v156 offset:3072
	ds_read_b128 v[202:205], v156 offset:4096
	ds_read_b128 v[206:209], v156 offset:5120
	ds_read_b128 v[210:213], v156 offset:6144
	ds_read_b128 v[214:217], v156 offset:7168
	global_load_lds_dwordx4 v[150:151], off
	v_lshl_add_u64 v[150:151], s[38:39], 0, v[140:141]
	s_add_i32 m0, s31, 0xe000
	s_nop 0
	global_load_lds_dwordx4 v[150:151], off
	s_cmp_lg_u32 s101, 0
	s_cbranch_scc1 .Lry7
	s_waitcnt vmcnt(8)
	s_branch .Lrk7

; #define PG8_STAGE(bufoff, gbase, voff) do { _Pragma("unroll") for (int _i = 0; _i < 2; ++_i) \
;         __builtin_amdgcn_global_load_lds((const unsigned*)((const char*)(gbase) + (voff)[_i]), (PG8_LAS unsigned*)(lds + (bufoff) + ldsw + _i * 8192), 16, 0, 0); } while (0)
; #define PG8_LDA(dst, b, h) do { _Pragma("unroll") for (int m = 0; m < 4; ++m) _Pragma("unroll") for (int k = 0; k < 2; ++k) dst[m][k] = *(const PG8_LAS bf16x8*)(lds + PG8_SA(b, h) + aoff + m * 2048 + k * 1024); } while (0)
; #define PG8_MMA(ai, bj, At, Bt) do { __builtin_amdgcn_s_setprio(1); _Pragma("unroll") for (int m = 0; m < 4; ++m) _Pragma("unroll") for (int n = 0; n < 2; ++n) _Pragma("unroll") for (int k = 0; k < 2; ++k) \
;         acc[ai][bj][m][n] = __builtin_amdgcn_mfma_f32_16x16x32_bf16(Bt[n][k], At[m][k], acc[ai][bj][m][n], 0, 0, 0); __builtin_amdgcn_s_setprio(0); } while (0)
; #define PG8_WAIT_V(n) asm volatile("s_waitcnt vmcnt(" #n ")" ::: "memory")
; #define PG8_WAIT_L(n) asm volatile("s_waitcnt lgkmcnt(" #n ")" ::: "memory")
; #define PG8_BAR __builtin_amdgcn_s_barrier()
; #define PG8_SCHED __builtin_amdgcn_sched_barrier(0)
; template <class Epi, class Sched, bool ALIGN_EPI = false, bool SP2 = false>
; __device__ __forceinline__ void gemm_phase(PG8_LAS unsigned char* lds, const Gemm g, const Sched& S, const Epi& E) {
;     ...
;             PG8_WAIT_V(8); PG8_WAIT_L(0); PG8_BAR; PG8_MMA(0, 0, At, B0); PG8_MMA(0, 1, At, B1); PG8_BAR; PG8_SCHED;
;             PG8_LDA(At, 0, 1); PG8_STAGE(PG8_SB(0, 0), b2, voffB); PG8_STAGE(PG8_SB(0, 1), b2 + hstepB, voffB); PG8_STAGE(PG8_SA(0, 0), a2, voffA);
;             PG8_WAIT_V(8); PG8_WAIT_L(0); PG8_BAR; PG8_MMA(1, 0, At, B0); PG8_MMA(1, 1, At, B1); PG8_BAR; PG8_SCHED;
.Lrk7:
	s_waitcnt lgkmcnt(0)
	s_barrier
	v_mfma_f32_16x16x32_bf16 v[126:129], v[146:149], v[186:189], v[126:129]
	v_mfma_f32_16x16x32_bf16 v[122:125], v[162:165], v[186:189], v[122:125]
	v_mfma_f32_16x16x32_bf16 v[110:113], v[146:149], v[194:197], v[110:113]
	v_mfma_f32_16x16x32_bf16 v[106:109], v[162:165], v[194:197], v[106:109]
	v_mfma_f32_16x16x32_bf16 v[94:97], v[146:149], v[202:205], v[94:97]
	v_mfma_f32_16x16x32_bf16 v[90:93], v[162:165], v[202:205], v[90:93]
	v_mfma_f32_16x16x32_bf16 v[78:81], v[146:149], v[210:213], v[78:81]
	v_mfma_f32_16x16x32_bf16 v[74:77], v[162:165], v[210:213], v[74:77]
	v_mfma_f32_16x16x32_bf16 v[126:129], v[158:161], v[190:193], v[126:129]
	v_mfma_f32_16x16x32_bf16 v[122:125], v[166:169], v[190:193], v[122:125]
	v_mfma_f32_16x16x32_bf16 v[110:113], v[158:161], v[198:201], v[110:113]
	v_mfma_f32_16x16x32_bf16 v[106:109], v[166:169], v[198:201], v[106:109]
	v_mfma_f32_16x16x32_bf16 v[94:97], v[158:161], v[206:209], v[94:97]
	v_mfma_f32_16x16x32_bf16 v[90:93], v[166:169], v[206:209], v[90:93]
	v_mfma_f32_16x16x32_bf16 v[78:81], v[158:161], v[214:217], v[78:81]
	v_mfma_f32_16x16x32_bf16 v[74:77], v[166:169], v[214:217], v[74:77]
	v_mfma_f32_16x16x32_bf16 v[118:121], v[170:173], v[186:189], v[118:121]
	v_mfma_f32_16x16x32_bf16 v[114:117], v[178:181], v[186:189], v[114:117]
	v_mfma_f32_16x16x32_bf16 v[102:105], v[170:173], v[194:197], v[102:105]
	v_mfma_f32_16x16x32_bf16 v[98:101], v[178:181], v[194:197], v[98:101]
	v_mfma_f32_16x16x32_bf16 v[86:89], v[170:173], v[202:205], v[86:89]
	v_mfma_f32_16x16x32_bf16 v[82:85], v[178:181], v[202:205], v[82:85]
	v_mfma_f32_16x16x32_bf16 v[70:73], v[170:173], v[210:213], v[70:73]
	v_mfma_f32_16x16x32_bf16 v[66:69], v[178:181], v[210:213], v[66:69]
	v_mfma_f32_16x16x32_bf16 v[118:121], v[174:177], v[190:193], v[118:121]
	v_mfma_f32_16x16x32_bf16 v[114:117], v[182:185], v[190:193], v[114:117]
	v_mfma_f32_16x16x32_bf16 v[102:105], v[174:177], v[198:201], v[102:105]
	v_mfma_f32_16x16x32_bf16 v[98:101], v[182:185], v[198:201], v[98:101]
	v_mfma_f32_16x16x32_bf16 v[86:89], v[174:177], v[206:209], v[86:89]
	v_mfma_f32_16x16x32_bf16 v[82:85], v[182:185], v[206:209], v[82:85]
	v_mfma_f32_16x16x32_bf16 v[70:73], v[174:177], v[214:217], v[70:73]
	v_mfma_f32_16x16x32_bf16 v[66:69], v[182:185], v[214:217], v[66:69]
	s_barrier
	s_add_i32 s62, s57, s30
	v_lshl_add_u64 v[150:151], s[40:41], 0, v[132:133]
	s_mov_b32 m0, s62
	ds_read_b128 v[186:189], v156 offset:16384
	ds_read_b128 v[190:193], v156 offset:17408
	ds_read_b128 v[194:197], v156 offset:18432
	ds_read_b128 v[198:201], v156 offset:19456
	ds_read_b128 v[202:205], v156 offset:20480
	ds_read_b128 v[206:209], v156 offset:21504
	ds_read_b128 v[210:213], v156 offset:22528
	ds_read_b128 v[214:217], v156 offset:23552
	global_load_lds_dwordx4 v[150:151], off
	s_add_i32 m0, s62, 0x2000
	s_add_u32 s62, s40, 0x10000
	v_lshl_add_u64 v[218:219], s[40:41], 0, v[136:137]
	s_addc_u32 s63, s41, 0
	s_add_i32 s64, s58, s30
	global_load_lds_dwordx4 v[218:219], off
	v_lshl_add_u64 v[220:221], s[62:63], 0, v[132:133]
	s_mov_b32 m0, s64
	v_lshl_add_u64 v[222:223], s[42:43], 0, v[134:135]
	global_load_lds_dwordx4 v[220:221], off
	v_lshl_add_u64 v[220:221], s[62:63], 0, v[136:137]
	s_add_i32 m0, s64, 0x2000
	s_nop 0
	global_load_lds_dwordx4 v[220:221], off
	v_lshl_add_u64 v[220:221], s[42:43], 0, v[130:131]
	s_mov_b32 m0, s31
	s_nop 0
	global_load_lds_dwordx4 v[220:221], off
	s_mov_b32 m0, s33
	s_nop 0
	global_load_lds_dwordx4 v[222:223], off
	s_cmp_lg_u32 s101, 0
	s_cbranch_scc1 .Lrx7
	s_waitcnt vmcnt(8)
	s_branch .Lrj7
